# attention: second inter-barrier block's 16 v_exp also moved into the first-half QK^T MFMA gaps (prologue hands over pre-exp values, tail does its own exps); first-half softmax VALU re-spaced evenly
# speedup vs baseline: 1.0088x; 1.0024x over previous
.LBB0_560:
	s_ashr_i32 s0, s4, 3
	s_and_b32 s14, s4, 7
	s_ashr_i32 s1, s0, 31
	s_lshl_b32 s4, s5, 8
	s_lshl_b64 s[46:47], s[0:1], 12
	s_and_b32 s4, s4, 0xf00
	s_or_b32 s46, s46, s4
	s_mul_i32 s4, s47, 0xc00
	s_mul_hi_u32 s5, s46, 0xc00
	s_add_i32 s5, s5, s4
	s_mul_i32 s4, s46, 0xc00
	s_add_u32 s6, s48, s4
	s_addc_u32 s7, s49, s5
	s_lshl_b32 s13, s14, 7
	s_lshl_b32 s4, s14, 8
	s_add_u32 s4, s6, s4
	s_addc_u32 s5, s7, 0
	s_barrier
	s_add_u32 s6, s6, s13
	v_mbcnt_lo_u32_b32 v60, -1, 0
	v_mbcnt_hi_u32_b32 v60, -1, v60
	s_addc_u32 s7, s7, 0
	v_or_b32_e32 v34, s33, v60
	v_ashrrev_i32_e32 v61, 1, v34
	s_movk_i32 s15, 0xffe0
	v_bfe_u32 v176, v60, 5, 1
	v_bfi_b32 v48, s15, v61, v60
	v_mov_b64_e32 v[0:1], s[6:7]
	v_lshlrev_b32_e32 v160, 4, v176
	v_mad_i64_i32 v[0:1], s[6:7], v48, s91, v[0:1]
	v_lshl_add_u64 v[12:13], v[0:1], 0, v[160:161]
	global_load_dwordx4 v[0:3], v[12:13], off offset:2048
	global_load_dwordx4 v[4:7], v[12:13], off offset:2080
	global_load_dwordx4 v[8:11], v[12:13], off offset:2112
	s_nop 0
	global_load_dwordx4 v[12:15], v[12:13], off offset:2144
	s_lshl_b64 s[6:7], s[0:1], 24
	s_add_u32 s16, s50, s6
	v_ashrrev_i32_e32 v36, 4, v34
	s_addc_u32 s17, s51, s7
	s_lshl_b32 s15, s14, 9
	v_add_u32_e32 v40, 32, v36
	s_add_u32 s16, s16, s15
	v_lshlrev_b32_e32 v49, 3, v34
	v_ashrrev_i32_e32 v37, 31, v36
	v_ashrrev_i32_e32 v41, 31, v40
	s_addc_u32 s17, s17, 0
	v_and_b32_e32 v16, 0x78, v49
	v_lshlrev_b64 v[52:53], 12, v[36:37]
	v_lshlrev_b64 v[20:21], 12, v[40:41]
	s_lshl_b64 s[0:1], s[0:1], 19
	v_ashrrev_i32_e32 v42, 3, v34
	v_lshlrev_b32_e32 v38, 1, v16
	v_lshl_add_u64 v[16:17], s[16:17], 0, v[52:53]
	v_lshl_add_u64 v[20:21], s[16:17], 0, v[20:21]
	s_add_u32 s16, s8, s0
	v_ashrrev_i32_e32 v43, 31, v42
	s_addc_u32 s17, s9, s1
	v_lshlrev_b64 v[54:55], 7, v[42:43]
	v_lshlrev_b32_e32 v34, 4, v34
	v_mov_b32_e32 v39, v161
	v_lshl_add_u64 v[32:33], s[16:17], 0, v[54:55]
	v_and_b32_e32 v44, 0x70, v34
	v_mov_b32_e32 v45, v161
	v_lshl_add_u64 v[56:57], v[16:17], 0, v[38:39]
	v_lshl_add_u64 v[28:29], v[20:21], 0, v[38:39]
	v_lshl_add_u64 v[58:59], v[32:33], 0, v[44:45]
	global_load_dwordx4 v[16:19], v[56:57], off offset:256
	global_load_dwordx4 v[24:27], v[56:57], off
	global_load_dwordx4 v[20:23], v[28:29], off offset:256
	global_load_dwordx4 v[32:35], v[58:59], off
	v_mov_b64_e32 v[46:47], s[4:5]
	global_load_dwordx4 v[28:31], v[28:29], off
	v_mad_i64_i32 v[46:47], s[4:5], v48, s91, v[46:47]
	v_lshl_add_u64 v[46:47], v[46:47], 0, v[160:161]
	global_load_dwordx4 v[120:123], v[46:47], off
	global_load_dwordx4 v[124:127], v[46:47], off offset:32
	global_load_dwordx4 v[116:119], v[46:47], off offset:64
	global_load_dwordx4 v[112:115], v[46:47], off offset:96
	global_load_dwordx4 v[108:111], v[46:47], off offset:128
	global_load_dwordx4 v[104:107], v[46:47], off offset:160
	global_load_dwordx4 v[100:103], v[46:47], off offset:192
	global_load_dwordx4 v[96:99], v[46:47], off offset:224
	v_lshlrev_b32_e32 v63, 4, v60
	s_add_i32 s5, 0, 0x14800
	v_and_b32_e32 v64, 0x70, v63
	v_and_b32_e32 v240, 0xf0, v63
	v_lshlrev_b32_e32 v241, 3, v60
	v_and_b32_e32 v241, 0x70, v241
	v_lshrrev_b32_e32 v242, 1, v60
	v_bitop3_b32 v37, v176, v242, 7 bitop3:0x78
	v_lshl_add_u32 v65, v48, 7, s5
	v_bitop3_b32 v39, v160, v241, 32 bitop3:0x36
	v_lshl_add_u32 v37, v37, 4, v65
	v_add_u32_e32 v184, v65, v39
	s_movk_i32 s5, 0x60
	v_mov_b32_e32 v62, s33
	s_movk_i32 s14, 0x70
	s_add_i32 s4, 0, 0x14000
	s_cmp_lg_u32 0, -1
	v_and_b32_e32 v177, 31, v60
	s_cselect_b32 s16, 0, 0
	v_or_b32_e32 v66, 64, v160
	v_or_b32_e32 v67, 0x60, v160
	s_waitcnt vmcnt(16)
	ds_write_b128 v37, v[0:3]
	s_waitcnt vmcnt(15)
	ds_write_b128 v184, v[4:7]
	v_bitop3_b32 v0, v160, v241, 64 bitop3:0x36
	v_add_u32_e32 v183, v65, v0
	v_bitop3_b32 v0, v160, v241, s5 bitop3:0x36
	v_add_u32_e32 v182, v65, v0
	v_and_b32_e32 v0, 0xfffff0, v36
	v_lshlrev_b32_e32 v1, 1, v36
	v_and_b32_e32 v4, 0xfffff0, v40
	v_lshlrev_b32_e32 v5, 1, v40
	v_and_or_b32 v0, v1, 8, v0
	v_and_or_b32 v4, v5, 8, v4
	v_lshrrev_b32_e32 v1, 1, v36
	v_lshrrev_b32_e32 v0, 1, v0
	v_bfe_u32 v2, v49, 5, 2
	v_and_b32_e32 v3, 3, v36
	v_lshrrev_b32_e32 v4, 1, v4
	v_or_b32_e32 v0, v0, v2
	v_and_or_b32 v1, v1, 4, v3
	v_or_b32_e32 v2, v4, v2
	v_lshlrev_b32_e32 v0, 9, v0
	v_lshlrev_b32_e32 v1, 6, v1
	v_and_b32_e32 v3, 48, v38
	v_lshlrev_b32_e32 v2, 9, v2
	v_or3_b32 v0, v0, v1, v3
	v_or3_b32 v1, v2, v1, v3
	v_add_u32_e32 v185, 0, v0
	v_add_u32_e32 v186, 0, v1
	v_lshlrev_b32_e32 v0, 8, v36
	v_bitop3_b32 v1, v60, s14, v62 bitop3:0xc8
	v_or_b32_e32 v243, s33, v60
	v_and_b32_e32 v243, 0xf0, v243
	v_bitop3_b32 v0, v38, v0, v243 bitop3:0xde
	v_add_u32_e32 v187, 0, v0
	v_lshlrev_b32_e32 v0, 8, v40
	v_bitop3_b32 v0, v38, v0, v243 bitop3:0xde
	v_lshlrev_b32_e32 v1, 3, v42
	v_add_u32_e32 v188, 0, v0
	v_lshlrev_b32_e32 v0, 7, v42
	v_and_b32_e32 v1, 0x70, v1
	v_mov_b32_e32 v242, v1
	v_bitop3_b32 v75, v44, v0, v1 bitop3:0xde
	s_add_i32 s5, 0, 0x10000
	s_waitcnt vmcnt(14)
	ds_write_b128 v183, v[8:11]
	s_waitcnt vmcnt(13)
	ds_write_b128 v182, v[12:15]
	v_add_u32_e32 v0, s5, v75
	v_lshlrev_b32_e32 v8, 8, v177
	s_waitcnt vmcnt(0)
	s_waitcnt vmcnt(12)
	ds_write_b128 v185, v[16:19]
	s_waitcnt vmcnt(10)
	ds_write_b128 v186, v[20:23]
	ds_write_b128 v187, v[24:27] offset:32768
	s_waitcnt vmcnt(8)
	ds_write_b128 v188, v[28:31] offset:32768
	ds_write_b128 v0, v[32:35]
	v_bitop3_b32 v0, v160, v8, v240 bitop3:0xde
	v_add_u32_e32 v189, 0, v0
	s_waitcnt lgkmcnt(0)
	s_barrier
	ds_read_b128 v[0:3], v189 offset:32768
	ds_read_b128 v[48:51], v182
	v_or_b32_e32 v12, 32, v160
	v_bitop3_b32 v4, v12, v8, v240 bitop3:0xde
	v_add_u32_e32 v190, 0, v4
	s_waitcnt vmcnt(7) lgkmcnt(1)
	v_mfma_f32_32x32x16_bf16 v[32:47], v[0:3], v[120:123], 0
	ds_read_b128 v[0:3], v189 offset:40960
	ds_read_b128 v[4:7], v190 offset:32768
	v_lshlrev_b32_e32 v68, 7, v177
	v_bitop3_b32 v198, v160, v68, v241 bitop3:0xde
	v_add_u32_e32 v199, s5, v198
	v_bitop3_b32 v200, v12, v68, v241 bitop3:0xde
	v_add_u32_e32 v201, s5, v200
	s_waitcnt vmcnt(6) lgkmcnt(0)
	v_mfma_f32_32x32x16_bf16 v[32:47], v[4:7], v[124:127], v[32:47]
	v_bitop3_b32 v4, v66, v8, v240 bitop3:0xde
	v_add_u32_e32 v191, 0, v4
	ds_read_b128 v[4:7], v191 offset:32768
	v_bitop3_b32 v202, v66, v68, v241 bitop3:0xde
	v_add_u32_e32 v203, s5, v202
	v_and_b32_e32 v76, 63, v60
	v_and_b32_e32 v156, 0xffffffe0, v61
	v_mfma_f32_32x32x16_bf16 v[16:31], v[0:3], v[120:123], 0
	ds_read_b128 v[0:3], v190 offset:40960
	v_lshlrev_b32_e32 v61, 3, v76
	v_bitop3_b32 v204, v67, v68, v241 bitop3:0xde
	v_add_u32_e32 v205, s5, v204
	v_readlane_b32 s68, v254, 50
	v_readlane_b32 s69, v254, 51
	s_mov_b32 s5, s69
	s_waitcnt vmcnt(5) lgkmcnt(1)
	v_mfma_f32_32x32x16_bf16 v[32:47], v[4:7], v[116:119], v[32:47]
	v_bitop3_b32 v4, v67, v8, v240 bitop3:0xde
	v_add_u32_e32 v192, 0, v4
	ds_read_b128 v[4:7], v192 offset:32768
	v_readlane_b32 s70, v254, 52
	v_readlane_b32 s71, v254, 53
	v_readlane_b32 s72, v254, 54
	v_readlane_b32 s73, v254, 55
	s_waitcnt lgkmcnt(1)
	v_mfma_f32_32x32x16_bf16 v[16:31], v[0:3], v[124:127], v[16:31]
	ds_read_b128 v[0:3], v191 offset:40960
	v_readlane_b32 s74, v254, 56
	v_readlane_b32 s75, v254, 57
	v_readlane_b32 s76, v254, 58
	v_readlane_b32 s77, v254, 59
	v_readlane_b32 s78, v254, 60
	v_readlane_b32 s79, v254, 61
	s_waitcnt vmcnt(4) lgkmcnt(1)
	v_mfma_f32_32x32x16_bf16 v[32:47], v[4:7], v[112:115], v[32:47]
	v_or_b32_e32 v4, 0x80, v160
	v_bitop3_b32 v4, v4, v8, v240 bitop3:0xde
	v_add_u32_e32 v193, 0, v4
	ds_read_b128 v[4:7], v193 offset:32768
	v_readlane_b32 s80, v254, 62
	v_readlane_b32 s81, v254, 63
	v_readlane_b32 s82, v255, 0
	s_waitcnt lgkmcnt(1)
	v_mfma_f32_32x32x16_bf16 v[16:31], v[0:3], v[116:119], v[16:31]
	ds_read_b128 v[0:3], v192 offset:40960
	v_readlane_b32 s83, v255, 1
	v_add_co_u32_e32 v66, vcc, s89, v56
	v_mov_b32_e32 v78, 0xf149f2ca
	s_nop 0
	v_addc_co_u32_e32 v67, vcc, 0, v57, vcc
	s_waitcnt vmcnt(3) lgkmcnt(1)
	v_mfma_f32_32x32x16_bf16 v[32:47], v[4:7], v[108:111], v[32:47]
	v_or_b32_e32 v4, 0xa0, v160
	v_bitop3_b32 v4, v4, v8, v240 bitop3:0xde
	v_add_u32_e32 v194, 0, v4
	ds_read_b128 v[4:7], v194 offset:32768
	s_mov_b32 s68, s69
	s_mov_b32 s70, s69
	s_mov_b32 s71, s69
	s_waitcnt lgkmcnt(1)
	v_mfma_f32_32x32x16_bf16 v[16:31], v[0:3], v[112:115], v[16:31]
	ds_read_b128 v[0:3], v193 offset:40960
	s_mov_b32 s72, s69
	s_mov_b32 s73, s69
	s_mov_b32 s74, s69
	s_mov_b32 s75, s69
	s_mov_b32 s76, s69
	s_mov_b32 s77, s69
	s_waitcnt lgkmcnt(0)
	v_mfma_f32_32x32x16_bf16 v[16:31], v[0:3], v[108:111], v[16:31]
	ds_read_b128 v[0:3], v194 offset:40960
	s_mov_b32 s78, s69
	s_mov_b32 s79, s69
	s_mov_b32 s80, s69
	s_mov_b32 s81, s69
	s_mov_b32 s82, s69
	s_mov_b32 s83, s69
	s_waitcnt vmcnt(2)
	v_mfma_f32_32x32x16_bf16 v[32:47], v[4:7], v[104:107], v[32:47]
	v_or_b32_e32 v4, 0xc0, v160
	v_bitop3_b32 v4, v4, v8, v240 bitop3:0xde
	v_add_u32_e32 v195, 0, v4
	ds_read_b128 v[4:7], v195 offset:32768
	v_add_u32_e32 v207, 0, v75
	v_add_u32_e32 v208, 0x12000, v207
	v_lshl_add_u64 v[170:171], s[0:1], 0, v[54:55]
	s_waitcnt lgkmcnt(1)
	v_mfma_f32_32x32x16_bf16 v[16:31], v[0:3], v[104:107], v[16:31]
	ds_read_b128 v[0:3], v195 offset:40960
	v_mov_b32_e32 v179, 0
	s_waitcnt vmcnt(1) lgkmcnt(1)
	v_mfma_f32_32x32x16_bf16 v[32:47], v[4:7], v[100:103], v[32:47]
	v_or_b32_e32 v4, 0xe0, v160
	v_bitop3_b32 v4, v4, v8, v240 bitop3:0xde
	v_add_u32_e32 v196, 0, v4
	ds_read_b128 v[4:7], v196 offset:32768
	s_waitcnt lgkmcnt(1)
	v_mfma_f32_32x32x16_bf16 v[16:31], v[0:3], v[100:103], v[16:31]
	ds_read_b128 v[0:3], v196 offset:40960
	s_waitcnt vmcnt(0) lgkmcnt(1)
	v_mfma_f32_32x32x16_bf16 v[32:47], v[4:7], v[96:99], v[32:47]
	ds_read_b128 v[4:7], v199
	s_waitcnt lgkmcnt(1)
	v_mfma_f32_32x32x16_bf16 v[16:31], v[0:3], v[96:99], v[16:31]
	v_xor_b32_e32 v0, v160, v241
	v_add_u32_e32 v197, v65, v0
	ds_read_b128 v[0:3], v197
	ds_read_b128 v[8:11], v199 offset:4096
	s_mov_b32 s14, 0x3fffffc0
	v_bitop3_b32 v62, v60, s14, v62 bitop3:0xc8
	v_lshl_add_u32 v157, v62, 2, s4
	v_and_b32_e32 v62, 0xc0, v63
	s_waitcnt lgkmcnt(1)
	v_mfma_f32_32x32x16_bf16 v[32:47], v[4:7], v[0:3], v[32:47]
	s_mov_b32 s14, -1
	v_lshl_add_u32 v178, v177, 2, v157
	s_waitcnt lgkmcnt(0)
	v_mfma_f32_32x32x16_bf16 v[16:31], v[8:11], v[0:3], v[16:31]
	ds_read_b128 v[0:3], v201
	ds_read_b128 v[4:7], v184
	ds_read_b128 v[8:11], v201 offset:4096
	ds_read_b128 v[12:15], v183
	s_waitcnt lgkmcnt(2)
	v_mfma_f32_32x32x16_bf16 v[32:47], v[0:3], v[4:7], v[32:47]
	ds_read_b128 v[0:3], v203
	s_waitcnt lgkmcnt(2)
	v_mfma_f32_32x32x16_bf16 v[16:31], v[8:11], v[4:7], v[16:31]
	v_lshlrev_b32_e32 v5, 1, v60
	v_and_or_b32 v4, v61, 24, v62
	v_and_b32_e32 v5, 32, v5
	v_and_b32_e32 v6, 0x100, v61
	v_or3_b32 v61, v4, v5, v6
	ds_read_b128 v[4:7], v203 offset:4096
	ds_read_b128 v[62:65], v205 offset:4096
	s_waitcnt lgkmcnt(2)
	v_mfma_f32_32x32x16_bf16 v[32:47], v[0:3], v[12:15], v[32:47]
	ds_read_b128 v[0:3], v205
	v_add_u32_e32 v181, s16, v61
	v_writelane_b32 v254, s4, 50
	s_nop 1
	v_writelane_b32 v255, s18, 0
	v_writelane_b32 v254, s5, 51
	s_waitcnt lgkmcnt(2)
	v_mfma_f32_32x32x16_bf16 v[16:31], v[4:7], v[12:15], v[16:31]
	v_writelane_b32 v255, s19, 1
	s_mov_b64 s[4:5], 0x40000
	v_writelane_b32 v254, s6, 52
	v_writelane_b32 v254, s7, 53
	v_writelane_b32 v254, s8, 54
	v_writelane_b32 v254, s9, 55
	v_writelane_b32 v254, s10, 56
	s_waitcnt lgkmcnt(0)
	v_mfma_f32_32x32x16_bf16 v[32:47], v[0:3], v[48:51], v[32:47]
	v_writelane_b32 v254, s11, 57
	v_writelane_b32 v254, s12, 58
	v_writelane_b32 v254, s13, 59
	v_writelane_b32 v254, s14, 60
	v_writelane_b32 v254, s15, 61
	v_mov_b64_e32 v[0:1], s[68:69]
	v_lshl_add_u64 v[158:159], s[6:7], 0, v[52:53]
	v_mfma_f32_32x32x16_bf16 v[16:31], v[62:65], v[48:51], v[16:31]
	s_nop 3
	v_max_f32_e32 v48, v33, v33
	v_max_f32_e32 v49, v32, v32
	v_max_f32_e32 v48, v49, v48
	v_max3_f32 v74, v48, v34, v35
	v_lshl_add_u64 v[48:49], v[56:57], 0, s[4:5]
	s_mov_b64 s[4:5], 0x60000
	v_lshl_add_u64 v[62:63], v[56:57], 0, s[4:5]
	s_mov_b32 s4, 0x60000
	v_add_co_u32_e32 v56, vcc, s4, v56
	global_load_dwordx4 v[48:51], v[48:49], off offset:256
	s_nop 0
	global_load_dwordx4 v[62:65], v[62:63], off offset:256
	v_addc_co_u32_e32 v57, vcc, 0, v57, vcc
	global_load_dwordx4 v[66:69], v[66:67], off
	s_nop 0
	global_load_dwordx4 v[70:73], v[56:57], off
	v_add_co_u32_e32 v56, vcc, s63, v58
	v_max3_f32 v74, v74, v36, v37
	s_nop 0
	v_addc_co_u32_e32 v57, vcc, 0, v59, vcc
	global_load_dwordx4 v[56:59], v[56:57], off
	v_max3_f32 v74, v74, v38, v39
	v_max3_f32 v74, v74, v40, v41
	v_max3_f32 v74, v74, v42, v43
	v_max3_f32 v74, v74, v44, v45
	v_max3_f32 v74, v74, v46, v47
	v_max3_f32 v74, v74, v16, v17
	v_max3_f32 v74, v74, v18, v19
	v_max3_f32 v74, v74, v20, v21
	v_max3_f32 v74, v74, v22, v23
	v_max3_f32 v74, v74, v24, v25
	v_max3_f32 v74, v74, v26, v27
	v_max3_f32 v74, v74, v28, v29
	v_max3_f32 v74, v74, v30, v31
	v_mov_b32_e32 v77, v74
	s_nop 1
	v_permlane32_swap_b32_e32 v74, v77
	v_max_f32_e32 v77, v77, v77
	v_max_f32_e32 v74, v74, v74
	v_max_f32_e32 v74, v74, v77
	v_add_f32_e32 v77, 0x7149f2ca, v74
	v_max_f32_e32 v74, 0xf149f2ca, v74
	v_cmp_ge_f32_e32 vcc, s90, v77
	v_sub_f32_e32 v77, 0xf149f2ca, v74
	v_mul_f32_e32 v77, 0x3dd53b94, v77
	v_exp_f32_e32 v77, v77
	s_cmp_eq_u64 vcc, exec
	s_cselect_b64 vcc, -1, 0
	v_cndmask_b32_e32 v209, v74, v78, vcc
	v_mul_f32_e32 v74, 0xbdd53b94, v209
	v_cndmask_b32_e64 v206, v77, 1.0, vcc
	v_mov_b32_e32 v77, v74
	v_fmamk_f32 v32, v32, 0x3dd53b94, v74
	v_fmamk_f32 v33, v33, 0x3dd53b94, v74
	v_fmamk_f32 v34, v34, 0x3dd53b94, v74
	v_fmamk_f32 v35, v35, 0x3dd53b94, v74
	v_fmamk_f32 v36, v36, 0x3dd53b94, v74
	v_fmamk_f32 v37, v37, 0x3dd53b94, v74
	v_fmamk_f32 v38, v38, 0x3dd53b94, v74
	v_fmamk_f32 v39, v39, 0x3dd53b94, v74
	v_fmamk_f32 v40, v40, 0x3dd53b94, v74
	v_fmamk_f32 v41, v41, 0x3dd53b94, v74
	v_fmamk_f32 v42, v42, 0x3dd53b94, v74
	v_fmamk_f32 v43, v43, 0x3dd53b94, v74
	v_fmamk_f32 v44, v44, 0x3dd53b94, v74
	v_fmamk_f32 v45, v45, 0x3dd53b94, v74
	v_fmamk_f32 v46, v46, 0x3dd53b94, v74
	v_fmac_f32_e32 v77, 0x3dd53b94, v47
	v_pk_fma_f32 v[140:141], v[16:17], s[60:61], v[74:75] op_sel_hi:[1,0,0]
	v_bitop3_b32 v16, v60, 15, s33 bitop3:0xc8
	v_mov_b32_e32 v175, v32
	v_mov_b32_e32 v217, v33
	v_mov_b32_e32 v149, v34
	v_mov_b32_e32 v216, v35
	v_mov_b32_e32 v150, v36
	v_mov_b32_e32 v174, v37
	v_mov_b32_e32 v151, v38
	v_mov_b32_e32 v173, v39
	v_mov_b32_e32 v154, v40
	v_mov_b32_e32 v172, v41
	v_mov_b32_e32 v153, v42
	v_mov_b32_e32 v155, v43
	v_mov_b32_e32 v145, v44
	v_mov_b32_e32 v147, v45
	v_mov_b32_e32 v144, v46
	v_mov_b32_e32 v146, v77
	v_lshlrev_b32_e32 v16, 4, v16
	v_writelane_b32 v254, s16, 62
	v_mov_b64_e32 v[14:15], s[82:83]
	s_waitcnt vmcnt(0)
	s_addk_i32 s16, 0x4000
	v_or3_b32 v158, v158, s15, v16
	v_bitop3_b32 v16, v60, 7, s33 bitop3:0xc8
	v_mov_b64_e32 v[2:3], s[70:71]
	v_mov_b64_e32 v[4:5], s[72:73]
	v_mov_b64_e32 v[6:7], s[74:75]
	v_mov_b64_e32 v[8:9], s[76:77]
	v_mov_b64_e32 v[10:11], s[78:79]
	v_mov_b64_e32 v[12:13], s[80:81]
	v_pk_fma_f32 v[134:135], v[30:31], s[60:61], v[74:75] op_sel_hi:[1,0,0]
	v_pk_fma_f32 v[136:137], v[28:29], s[60:61], v[74:75] op_sel_hi:[1,0,0]
	v_pk_fma_f32 v[142:143], v[26:27], s[60:61], v[74:75] op_sel_hi:[1,0,0]
	v_pk_fma_f32 v[128:129], v[24:25], s[60:61], v[74:75] op_sel_hi:[1,0,0]
	v_pk_fma_f32 v[130:131], v[22:23], s[60:61], v[74:75] op_sel_hi:[1,0,0]
	v_pk_fma_f32 v[132:133], v[20:21], s[60:61], v[74:75] op_sel_hi:[1,0,0]
	v_pk_fma_f32 v[138:139], v[18:19], s[60:61], v[74:75] op_sel_hi:[1,0,0]
	s_waitcnt vmcnt(4)
	ds_write_b128 v185, v[48:51] offset:16384
	s_waitcnt vmcnt(3)
	ds_write_b128 v186, v[62:65] offset:16384
	s_waitcnt vmcnt(2)
	ds_write_b128 v187, v[66:69] offset:49152
	s_waitcnt vmcnt(1)
	ds_write_b128 v188, v[70:73] offset:49152
	s_waitcnt vmcnt(0)
	ds_write_b128 v208, v[56:59]
	v_add_u32_e32 v180, s16, v61
	v_lshl_or_b32 v170, v16, 4, v170
	v_mov_b64_e32 v[62:63], v[14:15]
	v_mov_b64_e32 v[46:47], v[14:15]
	v_mov_b64_e32 v[30:31], v[14:15]
	v_writelane_b32 v254, s17, 63
	v_cmp_gt_u32_e64 s[4:5], 32, v76
	v_mov_b64_e32 v[60:61], v[12:13]
	v_mov_b64_e32 v[58:59], v[10:11]
	v_mov_b64_e32 v[56:57], v[8:9]
	v_mov_b64_e32 v[54:55], v[6:7]
	v_mov_b64_e32 v[52:53], v[4:5]
	v_mov_b64_e32 v[50:51], v[2:3]
	v_mov_b64_e32 v[48:49], v[0:1]
	v_mov_b64_e32 v[44:45], v[12:13]
	v_mov_b64_e32 v[42:43], v[10:11]
	v_mov_b64_e32 v[40:41], v[8:9]
	v_mov_b64_e32 v[38:39], v[6:7]
	v_mov_b64_e32 v[36:37], v[4:5]
	v_mov_b64_e32 v[34:35], v[2:3]
	v_mov_b64_e32 v[32:33], v[0:1]
	v_mov_b64_e32 v[28:29], v[12:13]
	v_mov_b64_e32 v[26:27], v[10:11]
	v_mov_b64_e32 v[24:25], v[8:9]
	v_mov_b64_e32 v[22:23], v[6:7]
	v_mov_b64_e32 v[20:21], v[4:5]
	v_mov_b64_e32 v[18:19], v[2:3]
	v_mov_b64_e32 v[16:17], v[0:1]
	s_waitcnt lgkmcnt(0)
	s_barrier
.LBB0_561:
	ds_read_b128 v[64:67], v189 offset:49152
	ds_read_b128 v[68:71], v189 offset:57344
	ds_read_b128 v[210:213], v190 offset:49152
	ds_read_b128 v[218:221], v190 offset:57344
	s_add_i32 s0, 0, 0x12000
	s_waitcnt lgkmcnt(3)
	v_mfma_f32_32x32x16_bf16 v[80:95], v[64:67], v[120:123], 0
	v_exp_f32_e32 v175, v175
	v_exp_f32_e32 v217, v217
	v_add_f32_e32 v148, 0, v175
	s_waitcnt lgkmcnt(2)
	v_mfma_f32_32x32x16_bf16 v[64:79], v[68:71], v[120:123], 0
	v_exp_f32_e32 v149, v149
	v_add_f32_e32 v148, v217, v148
	v_exp_f32_e32 v216, v216
	s_waitcnt lgkmcnt(1)
	v_mfma_f32_32x32x16_bf16 v[80:95], v[210:213], v[124:127], v[80:95]
	v_add_f32_e32 v148, v149, v148
	v_exp_f32_e32 v150, v150
	v_add_f32_e32 v148, v216, v148
	s_waitcnt lgkmcnt(0)
	v_mfma_f32_32x32x16_bf16 v[64:79], v[218:221], v[124:127], v[64:79]
	ds_read_b128 v[210:213], v191 offset:49152
	ds_read_b128 v[218:221], v191 offset:57344
	v_exp_f32_e32 v174, v174
	v_add_f32_e32 v148, v150, v148
	v_exp_f32_e32 v151, v151
	v_add_f32_e32 v148, v174, v148
	s_waitcnt lgkmcnt(1)
	v_mfma_f32_32x32x16_bf16 v[80:95], v[210:213], v[116:119], v[80:95]
	v_exp_f32_e32 v173, v173
	v_add_f32_e32 v148, v151, v148
	v_exp_f32_e32 v154, v154
	s_waitcnt lgkmcnt(0)
	v_mfma_f32_32x32x16_bf16 v[64:79], v[218:221], v[116:119], v[64:79]
	ds_read_b128 v[210:213], v192 offset:49152
	ds_read_b128 v[218:221], v192 offset:57344
	v_add_f32_e32 v148, v173, v148
	v_exp_f32_e32 v172, v172
	v_add_f32_e32 v148, v154, v148
	s_waitcnt lgkmcnt(1)
	v_mfma_f32_32x32x16_bf16 v[80:95], v[210:213], v[112:115], v[80:95]
	v_exp_f32_e32 v153, v153
	v_add_f32_e32 v148, v172, v148
	v_exp_f32_e32 v155, v155
	v_add_f32_e32 v148, v153, v148
	s_waitcnt lgkmcnt(0)
	v_mfma_f32_32x32x16_bf16 v[64:79], v[218:221], v[112:115], v[64:79]
	ds_read_b128 v[210:213], v193 offset:49152
	ds_read_b128 v[218:221], v193 offset:57344
	ds_read_b128 v[232:235], v194 offset:49152
	ds_read_b128 v[236:239], v194 offset:57344
	v_exp_f32_e32 v145, v145
	v_add_f32_e32 v148, v155, v148
	v_exp_f32_e32 v140, v140
	s_waitcnt lgkmcnt(3)
	v_mfma_f32_32x32x16_bf16 v[80:95], v[210:213], v[108:111], v[80:95]
	v_exp_f32_e32 v147, v147
	v_add_f32_e32 v148, v145, v148
	v_exp_f32_e32 v141, v141
	s_waitcnt lgkmcnt(2)
	v_mfma_f32_32x32x16_bf16 v[64:79], v[218:221], v[108:111], v[64:79]
	ds_read_b128 v[210:213], v195 offset:49152
	ds_read_b128 v[218:221], v195 offset:57344
	v_exp_f32_e32 v144, v144
	v_add_f32_e32 v148, v147, v148
	v_exp_f32_e32 v138, v138
	v_exp_f32_e32 v146, v146
	s_waitcnt lgkmcnt(3)
	v_mfma_f32_32x32x16_bf16 v[80:95], v[232:235], v[104:107], v[80:95]
	v_add_f32_e32 v148, v144, v148
	v_exp_f32_e32 v139, v139
	v_add_f32_e32 v148, v146, v148
	s_waitcnt lgkmcnt(2)
	v_mfma_f32_32x32x16_bf16 v[64:79], v[236:239], v[104:107], v[64:79]
	ds_read_b128 v[232:235], v196 offset:49152
	ds_read_b128 v[236:239], v196 offset:57344
	v_exp_f32_e32 v132, v132
	v_add_f32_e32 v148, v140, v148
	v_exp_f32_e32 v133, v133
	s_waitcnt lgkmcnt(3)
	v_mfma_f32_32x32x16_bf16 v[80:95], v[210:213], v[100:103], v[80:95]
	v_add_u32_e32 v230, s0, v198
	v_add_u32_e32 v231, s0, v200
	v_add_f32_e32 v148, v141, v148
	v_exp_f32_e32 v130, v130
	v_add_f32_e32 v148, v138, v148
	v_exp_f32_e32 v131, v131
	s_waitcnt lgkmcnt(2)
	v_mfma_f32_32x32x16_bf16 v[64:79], v[218:221], v[100:103], v[64:79]
	ds_read_b128 v[210:213], v230
	ds_read_b128 v[218:221], v230 offset:4096
	ds_read_b128 v[222:225], v197
	v_add_f32_e32 v148, v139, v148
	v_exp_f32_e32 v128, v128
	v_add_f32_e32 v148, v132, v148
	s_waitcnt lgkmcnt(4)
	v_mfma_f32_32x32x16_bf16 v[80:95], v[232:235], v[96:99], v[80:95]
	v_exp_f32_e32 v129, v129
	v_add_f32_e32 v148, v133, v148
	v_exp_f32_e32 v142, v142
	s_waitcnt lgkmcnt(3)
	v_mfma_f32_32x32x16_bf16 v[64:79], v[236:239], v[96:99], v[64:79]
	ds_read_b128 v[232:235], v231
	ds_read_b128 v[236:239], v231 offset:4096
	ds_read_b128 v[226:229], v184
	v_add_f32_e32 v148, v130, v148
	v_exp_f32_e32 v143, v143
	v_add_f32_e32 v148, v131, v148
	v_exp_f32_e32 v136, v136
	s_waitcnt lgkmcnt(3)
	v_mfma_f32_32x32x16_bf16 v[80:95], v[210:213], v[222:225], v[80:95]
	v_add_f32_e32 v148, v128, v148
	v_exp_f32_e32 v137, v137
	v_add_f32_e32 v148, v129, v148
	v_mfma_f32_32x32x16_bf16 v[64:79], v[218:221], v[222:225], v[64:79]
	v_add_u32_e32 v244, s0, v202
	v_add_u32_e32 v247, s0, v204
	ds_read_b128 v[210:213], v244
	ds_read_b128 v[218:221], v244 offset:4096
	ds_read_b128 v[222:225], v183
	v_exp_f32_e32 v134, v134
	v_add_f32_e32 v148, v142, v148
	v_exp_f32_e32 v135, v135
	s_waitcnt lgkmcnt(3)
	v_mfma_f32_32x32x16_bf16 v[80:95], v[232:235], v[226:229], v[80:95]
	v_add_f32_e32 v148, v143, v148
	v_add_f32_e32 v148, v136, v148
	v_add_f32_e32 v148, v137, v148
	v_add_f32_e32 v148, v134, v148
	v_add_f32_e32 v214, v135, v148
	v_mov_b32_e32 v215, v214
	s_nop 1
	v_permlane32_swap_b32_e32 v214, v215
	v_mfma_f32_32x32x16_bf16 v[64:79], v[236:239], v[226:229], v[64:79]
	ds_read_b128 v[232:235], v247
	ds_read_b128 v[236:239], v247 offset:4096
	ds_read_b128 v[226:229], v182
	s_waitcnt lgkmcnt(3)
	v_mfma_f32_32x32x16_bf16 v[80:95], v[210:213], v[222:225], v[80:95]
	v_mfma_f32_32x32x16_bf16 v[64:79], v[218:221], v[222:225], v[64:79]
	v_cvt_pk_bf16_f32 v148, v175, v217
	v_cvt_pk_bf16_f32 v149, v149, v216
	v_cvt_pk_bf16_f32 v150, v150, v174
	v_cvt_pk_bf16_f32 v151, v151, v173
	v_cvt_pk_bf16_f32 v152, v154, v172
	v_cvt_pk_bf16_f32 v153, v153, v155
	s_waitcnt lgkmcnt(0)
	v_mfma_f32_32x32x16_bf16 v[80:95], v[232:235], v[226:229], v[80:95]
	v_cvt_pk_bf16_f32 v154, v145, v147
	v_permlane32_swap_b32_e32 v148, v150
	v_cvt_pk_bf16_f32 v155, v144, v146
	v_permlane32_swap_b32_e32 v152, v154
	v_cvt_pk_bf16_f32 v216, v140, v141
	v_mfma_f32_32x32x16_bf16 v[64:79], v[236:239], v[226:229], v[64:79]
	v_cvt_pk_bf16_f32 v217, v138, v139
	v_cvt_pk_bf16_f32 v218, v132, v133
	v_cvt_pk_bf16_f32 v219, v130, v131
	v_cvt_pk_bf16_f32 v220, v128, v129
	v_cvt_pk_bf16_f32 v221, v142, v143
	v_cvt_pk_bf16_f32 v222, v136, v137
	v_cvt_pk_bf16_f32 v223, v134, v135
	v_permlane32_swap_b32_e32 v149, v151
	v_permlane32_swap_b32_e32 v153, v155
	v_permlane32_swap_b32_e32 v216, v218
	v_permlane32_swap_b32_e32 v217, v219
	v_permlane32_swap_b32_e32 v220, v222
	v_permlane32_swap_b32_e32 v221, v223
	v_lshl_add_u64 v[172:173], s[64:65], 0, v[158:159]
	s_mov_b32 s0, 0x34e80000
	v_add_co_u32_e32 v132, vcc, s0, v172
	s_mov_b32 s0, 0x34ea0000
	s_nop 0
	v_addc_co_u32_e32 v133, vcc, 0, v173, vcc
	v_add_co_u32_e32 v136, vcc, s0, v172
	v_lshl_add_u64 v[174:175], s[64:65], 0, v[170:171]
	s_nop 0
	v_addc_co_u32_e32 v137, vcc, 0, v173, vcc
	global_load_dwordx4 v[128:131], v[132:133], off offset:256
	s_nop 0
	v_xor_b32_e32 v134, v243, v132
	v_mov_b32_e32 v135, v133
	s_lshl_b32 s100, s33, 4
	s_add_i32 m0, s100, 0x8000
	s_nop 0
	global_load_lds_dwordx4 v[134:135], off
	s_nop 0
	global_load_dwordx4 v[140:143], v[136:137], off offset:256
	s_nop 0
	v_xor_b32_e32 v138, v243, v136
	v_mov_b32_e32 v139, v137
	s_add_i32 m0, s100, 0xa000
	s_nop 0
	global_load_lds_dwordx4 v[138:139], off
	s_mov_b32 s0, 0x1ea04000
	v_add_co_u32_e32 v144, vcc, s0, v174
	s_nop 1
	v_addc_co_u32_e32 v145, vcc, 0, v175, vcc
	v_xor_b32_e32 v144, v242, v144
	s_add_i32 m0, s100, 0x10000
	s_nop 0
	global_load_lds_dwordx4 v[144:145], off
	ds_read_b64_tr_b16 v[224:225], v181 offset:0
	ds_read_b64_tr_b16 v[226:227], v181 offset:0x800
	ds_read_b64_tr_b16 v[228:229], v181 offset:0x1000
	ds_read_b64_tr_b16 v[230:231], v181 offset:0x1800
	ds_read_b64_tr_b16 v[232:233], v181 offset:0x2000
	ds_read_b64_tr_b16 v[234:235], v181 offset:0x2800
	ds_read_b64_tr_b16 v[236:237], v181 offset:0x3000
	ds_read_b64_tr_b16 v[238:239], v181 offset:0x3800
	s_nop 0
	s_waitcnt lgkmcnt(6)
	v_mfma_f32_32x32x16_bf16 v[0:15], v[148:151], v[224:227], v[0:15]
	ds_read_b64_tr_b16 v[224:225], v181 offset:0x200
	ds_read_b64_tr_b16 v[226:227], v181 offset:0xa00
	s_waitcnt lgkmcnt(6)
	v_mfma_f32_32x32x16_bf16 v[0:15], v[152:155], v[228:231], v[0:15]
	ds_read_b64_tr_b16 v[228:229], v181 offset:0x1200
	ds_read_b64_tr_b16 v[230:231], v181 offset:0x1a00
	s_waitcnt lgkmcnt(6)
	v_mfma_f32_32x32x16_bf16 v[0:15], v[216:219], v[232:235], v[0:15]
	ds_read_b64_tr_b16 v[232:233], v181 offset:0x2200
	ds_read_b64_tr_b16 v[234:235], v181 offset:0x2a00
	s_waitcnt lgkmcnt(6)
	v_mfma_f32_32x32x16_bf16 v[0:15], v[220:223], v[236:239], v[0:15]
	ds_read_b64_tr_b16 v[236:237], v181 offset:0x3200
	ds_read_b64_tr_b16 v[238:239], v181 offset:0x3a00
	s_waitcnt lgkmcnt(6)
	v_mfma_f32_32x32x16_bf16 v[48:63], v[148:151], v[224:227], v[48:63]
	ds_read_b64_tr_b16 v[224:225], v181 offset:0x400
	ds_read_b64_tr_b16 v[226:227], v181 offset:0xc00
	s_waitcnt lgkmcnt(6)
	v_mfma_f32_32x32x16_bf16 v[48:63], v[152:155], v[228:231], v[48:63]
	ds_read_b64_tr_b16 v[228:229], v181 offset:0x1400
	ds_read_b64_tr_b16 v[230:231], v181 offset:0x1c00
	s_waitcnt lgkmcnt(6)
	v_mfma_f32_32x32x16_bf16 v[48:63], v[216:219], v[232:235], v[48:63]
	ds_read_b64_tr_b16 v[232:233], v181 offset:0x2400
	ds_read_b64_tr_b16 v[234:235], v181 offset:0x2c00
	s_waitcnt lgkmcnt(6)
	v_mfma_f32_32x32x16_bf16 v[48:63], v[220:223], v[236:239], v[48:63]
	ds_read_b64_tr_b16 v[236:237], v181 offset:0x3400
	ds_read_b64_tr_b16 v[238:239], v181 offset:0x3c00
	s_waitcnt lgkmcnt(6)
	v_mfma_f32_32x32x16_bf16 v[32:47], v[148:151], v[224:227], v[32:47]
	ds_read_b64_tr_b16 v[224:225], v181 offset:0x600
	ds_read_b64_tr_b16 v[226:227], v181 offset:0xe00
	s_waitcnt lgkmcnt(6)
	v_mfma_f32_32x32x16_bf16 v[32:47], v[152:155], v[228:231], v[32:47]
	ds_read_b64_tr_b16 v[228:229], v181 offset:0x1600
	ds_read_b64_tr_b16 v[230:231], v181 offset:0x1e00
	s_waitcnt lgkmcnt(6)
	v_mfma_f32_32x32x16_bf16 v[32:47], v[216:219], v[232:235], v[32:47]
	ds_read_b64_tr_b16 v[232:233], v181 offset:0x2600
	ds_read_b64_tr_b16 v[234:235], v181 offset:0x2e00
	s_waitcnt lgkmcnt(6)
	v_mfma_f32_32x32x16_bf16 v[32:47], v[220:223], v[236:239], v[32:47]
	ds_read_b64_tr_b16 v[236:237], v181 offset:0x3600
	ds_read_b64_tr_b16 v[238:239], v181 offset:0x3e00
	s_waitcnt lgkmcnt(6)
	v_mfma_f32_32x32x16_bf16 v[16:31], v[148:151], v[224:227], v[16:31]
	v_max_f32_e32 v148, v81, v81
	v_max_f32_e32 v149, v80, v80
	v_max_f32_e32 v148, v149, v148
	v_max3_f32 v148, v148, v82, v83
	v_max3_f32 v148, v148, v84, v85
	v_max3_f32 v148, v148, v86, v87
	v_max3_f32 v148, v148, v88, v89
	v_max3_f32 v148, v148, v90, v91
	v_max3_f32 v148, v148, v92, v93
	s_waitcnt lgkmcnt(4)
	v_mfma_f32_32x32x16_bf16 v[16:31], v[152:155], v[228:231], v[16:31]
	v_max3_f32 v148, v148, v94, v95
	v_max3_f32 v148, v148, v64, v65
	v_max3_f32 v148, v148, v66, v67
	v_max3_f32 v148, v148, v68, v69
	v_max3_f32 v148, v148, v70, v71
	v_max3_f32 v148, v148, v72, v73
	v_max3_f32 v148, v148, v74, v75
	v_max3_f32 v148, v148, v76, v77
	s_waitcnt lgkmcnt(2)
	v_mfma_f32_32x32x16_bf16 v[16:31], v[216:219], v[232:235], v[16:31]
	v_max3_f32 v148, v148, v78, v79
	v_mov_b32_e32 v149, v148
	s_nop 1
	v_permlane32_swap_b32_e32 v148, v149
	v_max_f32_e32 v149, v149, v149
	v_max_f32_e32 v148, v148, v148
	v_max_f32_e32 v148, v148, v149
	v_sub_f32_e32 v149, v148, v209
	v_cmp_ge_f32_e32 vcc, s90, v149
	v_max_f32_e32 v149, v209, v209
	v_max_f32_e32 v148, v149, v148
	s_waitcnt lgkmcnt(0)
	v_mfma_f32_32x32x16_bf16 v[16:31], v[220:223], v[236:239], v[16:31]
	v_sub_f32_e32 v149, v209, v148
	v_mul_f32_e32 v149, 0x3dd53b94, v149
	v_exp_f32_e32 v149, v149
	s_cmp_eq_u64 vcc, exec
	s_cselect_b64 s[6:7], -1, 0
	s_barrier
	s_waitcnt vmcnt(0)
	v_cndmask_b32_e64 v152, v149, 1.0, s[6:7]
	s_waitcnt vmcnt(4)
	ds_write_b128 v185, v[128:131]
	s_waitcnt vmcnt(2)
	ds_write_b128 v186, v[140:143]
	s_waitcnt vmcnt(1)
	v_add_u32_e32 v128, 0x10000, v207
	v_cmp_gt_f32_e32 vcc, 1.0, v152
	s_waitcnt vmcnt(0)
	s_cbranch_vccz .LBB0_565
	s_and_saveexec_b64 s[0:1], s[4:5]
	ds_write_b32 v178, v152 offset:128
	s_or_b64 exec, exec, s[0:1]
	s_waitcnt lgkmcnt(0)
	v_add_u32_e32 v140, v157, v160
	ds_read_b128 v[128:131], v140 offset:224
	ds_read_b128 v[132:135], v140 offset:192
	ds_read_b128 v[136:139], v140 offset:160
	ds_read_b128 v[140:143], v140 offset:128
	s_waitcnt lgkmcnt(3)
	v_pk_mul_f32 v[12:13], v[12:13], v[128:129]
	s_waitcnt lgkmcnt(2)
	v_pk_mul_f32 v[8:9], v[8:9], v[132:133]
	s_waitcnt lgkmcnt(1)
	v_pk_mul_f32 v[4:5], v[4:5], v[136:137]
	v_pk_mul_f32 v[14:15], v[14:15], v[130:131]
	v_pk_mul_f32 v[10:11], v[10:11], v[134:135]
	v_pk_mul_f32 v[6:7], v[6:7], v[138:139]
	s_waitcnt lgkmcnt(0)
	v_pk_mul_f32 v[2:3], v[2:3], v[142:143]
	v_pk_mul_f32 v[0:1], v[0:1], v[140:141]
	v_pk_mul_f32 v[60:61], v[60:61], v[128:129]
	v_pk_mul_f32 v[56:57], v[56:57], v[132:133]
	v_pk_mul_f32 v[52:53], v[52:53], v[136:137]
	v_pk_mul_f32 v[62:63], v[62:63], v[130:131]
	v_pk_mul_f32 v[58:59], v[58:59], v[134:135]
	v_pk_mul_f32 v[54:55], v[54:55], v[138:139]
	v_pk_mul_f32 v[50:51], v[50:51], v[142:143]
	v_pk_mul_f32 v[48:49], v[48:49], v[140:141]
	v_pk_mul_f32 v[44:45], v[44:45], v[128:129]
	v_pk_mul_f32 v[40:41], v[40:41], v[132:133]
	v_pk_mul_f32 v[36:37], v[36:37], v[136:137]
	v_pk_mul_f32 v[46:47], v[46:47], v[130:131]
	v_pk_mul_f32 v[42:43], v[42:43], v[134:135]
	v_pk_mul_f32 v[38:39], v[38:39], v[138:139]
	v_pk_mul_f32 v[34:35], v[34:35], v[142:143]
	v_pk_mul_f32 v[32:33], v[32:33], v[140:141]
	v_pk_mul_f32 v[28:29], v[28:29], v[128:129]
	v_pk_mul_f32 v[24:25], v[24:25], v[132:133]
	v_pk_mul_f32 v[20:21], v[20:21], v[136:137]
	v_pk_mul_f32 v[30:31], v[30:31], v[130:131]
	v_pk_mul_f32 v[26:27], v[26:27], v[134:135]
	v_pk_mul_f32 v[22:23], v[22:23], v[138:139]
	v_pk_mul_f32 v[18:19], v[18:19], v[142:143]
	v_pk_mul_f32 v[16:17], v[16:17], v[140:141]

.LBB0_569:
	v_cndmask_b32_e64 v209, v149, v153, s[6:7]
	v_mul_f32_e32 v134, 0xbdd53b94, v209
	v_mov_b32_e32 v135, v134
	v_fmamk_f32 v175, v80, 0x3dd53b94, v134
	v_fmamk_f32 v217, v81, 0x3dd53b94, v134
	v_fmamk_f32 v149, v82, 0x3dd53b94, v134
	v_fmamk_f32 v216, v83, 0x3dd53b94, v134
	v_fmamk_f32 v150, v84, 0x3dd53b94, v134
	v_fmamk_f32 v174, v85, 0x3dd53b94, v134
	v_fmamk_f32 v151, v86, 0x3dd53b94, v134
	v_fmamk_f32 v173, v87, 0x3dd53b94, v134
	v_fmamk_f32 v154, v88, 0x3dd53b94, v134
	v_fmamk_f32 v172, v89, 0x3dd53b94, v134
	v_fmamk_f32 v153, v90, 0x3dd53b94, v134
	v_fmamk_f32 v155, v91, 0x3dd53b94, v134
	v_fmamk_f32 v145, v92, 0x3dd53b94, v134
	v_fmamk_f32 v147, v93, 0x3dd53b94, v134
	v_fmamk_f32 v144, v94, 0x3dd53b94, v134
	v_fmamk_f32 v146, v95, 0x3dd53b94, v134
	v_pk_fma_f32 v[140:141], v[64:65], s[60:61], v[134:135] op_sel_hi:[1,0,0]
	v_add_f32_e32 v64, v214, v215
	v_fmac_f32_e32 v64, v206, v179
	v_add_f32_e32 v179, v218, v219
	s_add_i32 s14, s14, 2
	s_mov_b64 s[0:1], 0x80000
	v_pk_fma_f32 v[138:139], v[66:67], s[60:61], v[134:135] op_sel_hi:[1,0,0]
	v_pk_fma_f32 v[132:133], v[68:69], s[60:61], v[134:135] op_sel_hi:[1,0,0]
	v_pk_fma_f32 v[130:131], v[70:71], s[60:61], v[134:135] op_sel_hi:[1,0,0]
	v_pk_fma_f32 v[128:129], v[72:73], s[60:61], v[134:135] op_sel_hi:[1,0,0]
	v_pk_fma_f32 v[142:143], v[74:75], s[60:61], v[134:135] op_sel_hi:[1,0,0]
	v_pk_fma_f32 v[136:137], v[76:77], s[60:61], v[134:135] op_sel_hi:[1,0,0]
	v_pk_fma_f32 v[134:135], v[78:79], s[60:61], v[134:135] op_sel_hi:[1,0,0]
	v_fmac_f32_e32 v179, v64, v152
	v_lshl_add_u64 v[158:159], v[158:159], 0, s[0:1]
	s_cmp_gt_u32 s14, 60
	v_lshl_add_u64 v[170:171], v[170:171], 0, s[10:11]
	s_waitcnt lgkmcnt(0)
	s_barrier
	s_cbranch_scc1 .LBB0_571
	v_mov_b32_e32 v206, v148
	s_branch .LBB0_561
.LBB0_571:
	ds_read_b128 v[64:67], v189 offset:49152
	ds_read_b128 v[68:71], v189 offset:57344
	v_exp_f32_e32 v175, v175
	v_exp_f32_e32 v217, v217
	v_exp_f32_e32 v149, v149
	v_exp_f32_e32 v216, v216
	v_exp_f32_e32 v150, v150
	v_exp_f32_e32 v174, v174
	v_exp_f32_e32 v151, v151
	v_exp_f32_e32 v173, v173
	v_exp_f32_e32 v154, v154
	v_exp_f32_e32 v172, v172
	v_exp_f32_e32 v153, v153
	v_exp_f32_e32 v155, v155
	v_exp_f32_e32 v145, v145
	v_exp_f32_e32 v147, v147
	v_exp_f32_e32 v144, v144
	v_exp_f32_e32 v146, v146
	s_waitcnt lgkmcnt(1)
	v_mfma_f32_32x32x16_bf16 v[80:95], v[64:67], v[120:123], 0
	s_waitcnt lgkmcnt(0)
	v_mfma_f32_32x32x16_bf16 v[64:79], v[68:71], v[120:123], 0
	ds_read_b128 v[120:123], v190 offset:49152
	ds_read_b128 v[186:189], v190 offset:57344
	s_waitcnt lgkmcnt(1)
	v_mfma_f32_32x32x16_bf16 v[80:95], v[120:123], v[124:127], v[80:95]
	s_waitcnt lgkmcnt(0)
	v_mfma_f32_32x32x16_bf16 v[64:79], v[186:189], v[124:127], v[64:79]
	ds_read_b128 v[120:123], v191 offset:49152
	ds_read_b128 v[124:127], v191 offset:57344
	s_waitcnt lgkmcnt(1)
	v_mfma_f32_32x32x16_bf16 v[80:95], v[120:123], v[116:119], v[80:95]
	s_waitcnt lgkmcnt(0)
	v_mfma_f32_32x32x16_bf16 v[64:79], v[124:127], v[116:119], v[64:79]
	ds_read_b128 v[116:119], v192 offset:49152
	ds_read_b128 v[120:123], v192 offset:57344
	s_waitcnt lgkmcnt(1)
	v_mfma_f32_32x32x16_bf16 v[80:95], v[116:119], v[112:115], v[80:95]
	s_waitcnt lgkmcnt(0)
	v_mfma_f32_32x32x16_bf16 v[64:79], v[120:123], v[112:115], v[64:79]
	ds_read_b128 v[112:115], v193 offset:49152
	ds_read_b128 v[116:119], v193 offset:57344
	v_exp_f32_e32 v120, v134
	v_exp_f32_e32 v121, v135
	s_waitcnt lgkmcnt(1)
	v_mfma_f32_32x32x16_bf16 v[80:95], v[112:115], v[108:111], v[80:95]
	s_waitcnt lgkmcnt(0)
	v_mfma_f32_32x32x16_bf16 v[64:79], v[116:119], v[108:111], v[64:79]
	ds_read_b128 v[108:111], v194 offset:49152
	ds_read_b128 v[112:115], v194 offset:57344
	v_exp_f32_e32 v116, v142
	v_exp_f32_e32 v117, v143
	v_exp_f32_e32 v118, v136
	v_exp_f32_e32 v119, v137
	s_waitcnt lgkmcnt(1)
	v_mfma_f32_32x32x16_bf16 v[80:95], v[108:111], v[104:107], v[80:95]
	s_waitcnt lgkmcnt(0)
	v_mfma_f32_32x32x16_bf16 v[64:79], v[112:115], v[104:107], v[64:79]
	ds_read_b128 v[104:107], v195 offset:49152
	ds_read_b128 v[108:111], v195 offset:57344
	v_exp_f32_e32 v112, v130
	v_exp_f32_e32 v113, v131
	v_exp_f32_e32 v114, v128
	v_exp_f32_e32 v115, v129
	s_waitcnt lgkmcnt(1)
	v_mfma_f32_32x32x16_bf16 v[80:95], v[104:107], v[100:103], v[80:95]
	s_waitcnt lgkmcnt(0)
	v_mfma_f32_32x32x16_bf16 v[64:79], v[108:111], v[100:103], v[64:79]
	ds_read_b128 v[100:103], v196 offset:49152
	ds_read_b128 v[104:107], v196 offset:57344
	v_exp_f32_e32 v108, v138
	v_exp_f32_e32 v109, v139
	v_exp_f32_e32 v110, v132
	v_exp_f32_e32 v111, v133
	s_waitcnt lgkmcnt(1)
	v_mfma_f32_32x32x16_bf16 v[80:95], v[100:103], v[96:99], v[80:95]
	s_waitcnt lgkmcnt(0)
	v_mfma_f32_32x32x16_bf16 v[64:79], v[104:107], v[96:99], v[64:79]
	ds_read_b128 v[96:99], v210
	ds_read_b128 v[100:103], v210 offset:4096
	ds_read_b128 v[104:107], v197
	s_waitcnt lgkmcnt(0)
	v_mfma_f32_32x32x16_bf16 v[80:95], v[96:99], v[104:107], v[80:95]
	v_mfma_f32_32x32x16_bf16 v[64:79], v[100:103], v[104:107], v[64:79]
	ds_read_b128 v[96:99], v211
	ds_read_b128 v[100:103], v211 offset:4096
	ds_read_b128 v[104:107], v184
	s_waitcnt lgkmcnt(0)
	v_mfma_f32_32x32x16_bf16 v[80:95], v[96:99], v[104:107], v[80:95]
	v_mfma_f32_32x32x16_bf16 v[64:79], v[100:103], v[104:107], v[64:79]
	ds_read_b128 v[96:99], v212
	ds_read_b128 v[100:103], v212 offset:4096
	ds_read_b128 v[104:107], v183
	s_waitcnt lgkmcnt(0)
	v_mfma_f32_32x32x16_bf16 v[80:95], v[96:99], v[104:107], v[80:95]
	v_mfma_f32_32x32x16_bf16 v[64:79], v[100:103], v[104:107], v[64:79]
	ds_read_b128 v[96:99], v213
	ds_read_b128 v[100:103], v213 offset:4096
	ds_read_b128 v[104:107], v182
	s_waitcnt lgkmcnt(0)
	v_mfma_f32_32x32x16_bf16 v[80:95], v[96:99], v[104:107], v[80:95]
	v_add_f32_e32 v96, 0, v175
	v_add_f32_e32 v96, v217, v96
	v_add_f32_e32 v96, v149, v96
	v_add_f32_e32 v96, v216, v96
	v_add_f32_e32 v96, v150, v96
	v_add_f32_e32 v96, v174, v96
	v_add_f32_e32 v96, v151, v96
	v_add_f32_e32 v96, v173, v96
	v_add_f32_e32 v96, v154, v96
	v_add_f32_e32 v96, v172, v96
	v_add_f32_e32 v96, v153, v96
	v_add_f32_e32 v96, v155, v96
	v_mfma_f32_32x32x16_bf16 v[64:79], v[100:103], v[104:107], v[64:79]
	v_exp_f32_e32 v106, v140
	v_add_f32_e32 v96, v145, v96
	v_exp_f32_e32 v107, v141
	v_add_f32_e32 v96, v147, v96
	v_add_f32_e32 v96, v144, v96
	v_add_f32_e32 v96, v146, v96
	v_add_f32_e32 v96, v106, v96
	v_add_f32_e32 v96, v107, v96
	v_add_f32_e32 v96, v108, v96
	v_add_f32_e32 v96, v109, v96
	v_add_f32_e32 v96, v110, v96
	v_add_f32_e32 v96, v111, v96
	v_add_f32_e32 v96, v112, v96
	v_add_f32_e32 v96, v113, v96
	v_add_f32_e32 v96, v114, v96
	v_add_f32_e32 v96, v115, v96
	v_add_f32_e32 v96, v116, v96
	v_add_f32_e32 v96, v117, v96
	v_add_f32_e32 v96, v118, v96
	v_add_f32_e32 v96, v119, v96
	v_add_f32_e32 v96, v120, v96
	v_add_f32_e32 v100, v121, v96
	v_mov_b32_e32 v101, v100
	v_cvt_pk_bf16_f32 v96, v175, v217
	v_cvt_pk_bf16_f32 v97, v149, v216
	v_cvt_pk_bf16_f32 v98, v150, v174
	v_cvt_pk_bf16_f32 v99, v151, v173
	s_nop 1
	v_permlane32_swap_b32_e32 v100, v101
	v_permlane32_swap_b32_e32 v96, v98
	v_permlane32_swap_b32_e32 v97, v99
	v_cvt_pk_bf16_f32 v102, v154, v172
	v_cvt_pk_bf16_f32 v103, v153, v155
	v_cvt_pk_bf16_f32 v104, v145, v147
	v_cvt_pk_bf16_f32 v105, v144, v146
	v_cvt_pk_bf16_f32 v106, v106, v107
	v_cvt_pk_bf16_f32 v107, v108, v109
	v_cvt_pk_bf16_f32 v108, v110, v111
	v_cvt_pk_bf16_f32 v109, v112, v113
	v_cvt_pk_bf16_f32 v110, v114, v115
	v_cvt_pk_bf16_f32 v111, v116, v117
	v_cvt_pk_bf16_f32 v112, v118, v119
	v_cvt_pk_bf16_f32 v113, v120, v121
	s_nop 0
	v_permlane32_swap_b32_e32 v102, v104
	v_permlane32_swap_b32_e32 v103, v105
	v_permlane32_swap_b32_e32 v106, v108
	v_permlane32_swap_b32_e32 v107, v109
	v_permlane32_swap_b32_e32 v110, v112
	v_permlane32_swap_b32_e32 v111, v113
	ds_read_b64_tr_b16 v[114:115], v181 offset:0
	ds_read_b64_tr_b16 v[116:117], v181 offset:0x800
	ds_read_b64_tr_b16 v[118:119], v181 offset:0x1000
	ds_read_b64_tr_b16 v[120:121], v181 offset:0x1800
	ds_read_b64_tr_b16 v[122:123], v181 offset:0x2000
	ds_read_b64_tr_b16 v[124:125], v181 offset:0x2800
	ds_read_b64_tr_b16 v[126:127], v181 offset:0x3000
	ds_read_b64_tr_b16 v[128:129], v181 offset:0x3800
	s_waitcnt lgkmcnt(0)
	s_nop 0
	v_mfma_f32_32x32x16_bf16 v[0:15], v[96:99], v[114:117], v[0:15]
	ds_read_b64_tr_b16 v[114:115], v181 offset:0x200
	ds_read_b64_tr_b16 v[116:117], v181 offset:0xa00
	v_mfma_f32_32x32x16_bf16 v[0:15], v[102:105], v[118:121], v[0:15]
	ds_read_b64_tr_b16 v[118:119], v181 offset:0x1200
	ds_read_b64_tr_b16 v[120:121], v181 offset:0x1a00
	v_mfma_f32_32x32x16_bf16 v[0:15], v[106:109], v[122:125], v[0:15]
	ds_read_b64_tr_b16 v[122:123], v181 offset:0x2200
	ds_read_b64_tr_b16 v[124:125], v181 offset:0x2a00
	v_mfma_f32_32x32x16_bf16 v[0:15], v[110:113], v[126:129], v[0:15]
	ds_read_b64_tr_b16 v[126:127], v181 offset:0x3200
	ds_read_b64_tr_b16 v[128:129], v181 offset:0x3a00
	s_waitcnt lgkmcnt(0)
	v_mfma_f32_32x32x16_bf16 v[48:63], v[96:99], v[114:117], v[48:63]
	ds_read_b64_tr_b16 v[114:115], v181 offset:0x400
	ds_read_b64_tr_b16 v[116:117], v181 offset:0xc00
	v_mfma_f32_32x32x16_bf16 v[48:63], v[102:105], v[118:121], v[48:63]
	ds_read_b64_tr_b16 v[118:119], v181 offset:0x1400
	ds_read_b64_tr_b16 v[120:121], v181 offset:0x1c00
	v_mfma_f32_32x32x16_bf16 v[48:63], v[106:109], v[122:125], v[48:63]
	ds_read_b64_tr_b16 v[122:123], v181 offset:0x2400
	ds_read_b64_tr_b16 v[124:125], v181 offset:0x2c00
	v_mfma_f32_32x32x16_bf16 v[48:63], v[110:113], v[126:129], v[48:63]
	ds_read_b64_tr_b16 v[126:127], v181 offset:0x3400
	ds_read_b64_tr_b16 v[128:129], v181 offset:0x3c00
	s_waitcnt lgkmcnt(0)
	v_mfma_f32_32x32x16_bf16 v[32:47], v[96:99], v[114:117], v[32:47]
	ds_read_b64_tr_b16 v[114:115], v181 offset:0x600
	ds_read_b64_tr_b16 v[116:117], v181 offset:0xe00
	v_mfma_f32_32x32x16_bf16 v[32:47], v[102:105], v[118:121], v[32:47]
	ds_read_b64_tr_b16 v[118:119], v181 offset:0x1600
	ds_read_b64_tr_b16 v[120:121], v181 offset:0x1e00
	v_mfma_f32_32x32x16_bf16 v[32:47], v[106:109], v[122:125], v[32:47]
	ds_read_b64_tr_b16 v[122:123], v181 offset:0x2600
	ds_read_b64_tr_b16 v[124:125], v181 offset:0x2e00
	v_mfma_f32_32x32x16_bf16 v[32:47], v[110:113], v[126:129], v[32:47]
	ds_read_b64_tr_b16 v[126:127], v181 offset:0x3600
	ds_read_b64_tr_b16 v[128:129], v181 offset:0x3e00
	s_waitcnt lgkmcnt(0)
	v_mfma_f32_32x32x16_bf16 v[16:31], v[96:99], v[114:117], v[16:31]
	v_max_f32_e32 v96, v81, v81
	v_max_f32_e32 v97, v80, v80
	v_max_f32_e32 v96, v97, v96
	v_max3_f32 v96, v96, v82, v83
	v_max3_f32 v96, v96, v84, v85
	v_max3_f32 v96, v96, v86, v87
	v_max3_f32 v96, v96, v88, v89
	v_max3_f32 v96, v96, v90, v91
	v_max3_f32 v96, v96, v92, v93
	v_mfma_f32_32x32x16_bf16 v[16:31], v[102:105], v[118:121], v[16:31]
	v_max3_f32 v96, v96, v94, v95
	v_max3_f32 v96, v96, v64, v65
	v_max3_f32 v96, v96, v66, v67
	v_max3_f32 v96, v96, v68, v69
	v_max3_f32 v96, v96, v70, v71
	v_max3_f32 v96, v96, v72, v73
	v_max3_f32 v96, v96, v74, v75
	v_max3_f32 v96, v96, v76, v77
	v_mfma_f32_32x32x16_bf16 v[16:31], v[106:109], v[122:125], v[16:31]
	v_max3_f32 v96, v96, v78, v79
	v_mov_b32_e32 v97, v96
	s_nop 1
	v_permlane32_swap_b32_e32 v96, v97
	v_max_f32_e32 v97, v97, v97
	v_max_f32_e32 v96, v96, v96
	v_max_f32_e32 v96, v96, v97
	v_sub_f32_e32 v97, v96, v209
	v_cmp_ge_f32_e32 vcc, s90, v97
	v_max_f32_e32 v97, v209, v209
	v_max_f32_e32 v97, v97, v96
	v_mfma_f32_32x32x16_bf16 v[16:31], v[110:113], v[126:129], v[16:31]
	v_sub_f32_e32 v96, v209, v97
	v_mul_f32_e32 v96, 0x3dd53b94, v96
	v_exp_f32_e32 v96, v96
	s_cmp_eq_u64 vcc, exec
	s_cselect_b64 s[6:7], -1, 0
	v_cndmask_b32_e64 v96, v96, 1.0, s[6:7]
	v_cmp_gt_f32_e32 vcc, 1.0, v96
	s_barrier
	s_cbranch_vccz .LBB0_575
	s_and_saveexec_b64 s[0:1], s[4:5]
	ds_write_b32 v178, v96 offset:128
	s_or_b64 exec, exec, s[0:1]
	s_waitcnt lgkmcnt(0)
	v_add_u32_e32 v98, v157, v160
	ds_read_b128 v[102:105], v98 offset:224
	ds_read_b128 v[106:109], v98 offset:192
	ds_read_b128 v[110:113], v98 offset:160
	ds_read_b128 v[114:117], v98 offset:128
	s_waitcnt lgkmcnt(3)
	v_pk_mul_f32 v[12:13], v[12:13], v[102:103]
	s_waitcnt lgkmcnt(2)
	v_pk_mul_f32 v[8:9], v[8:9], v[106:107]
	s_waitcnt lgkmcnt(1)
	v_pk_mul_f32 v[4:5], v[4:5], v[110:111]
	v_pk_mul_f32 v[14:15], v[14:15], v[104:105]
	v_pk_mul_f32 v[10:11], v[10:11], v[108:109]
	v_pk_mul_f32 v[6:7], v[6:7], v[112:113]
	s_waitcnt lgkmcnt(0)
	v_pk_mul_f32 v[2:3], v[2:3], v[116:117]
	v_pk_mul_f32 v[0:1], v[0:1], v[114:115]
	v_pk_mul_f32 v[60:61], v[60:61], v[102:103]
	v_pk_mul_f32 v[56:57], v[56:57], v[106:107]
	v_pk_mul_f32 v[52:53], v[52:53], v[110:111]
	v_pk_mul_f32 v[62:63], v[62:63], v[104:105]
	v_pk_mul_f32 v[58:59], v[58:59], v[108:109]
	v_pk_mul_f32 v[54:55], v[54:55], v[112:113]
	v_pk_mul_f32 v[50:51], v[50:51], v[116:117]
	v_pk_mul_f32 v[48:49], v[48:49], v[114:115]
	v_pk_mul_f32 v[44:45], v[44:45], v[102:103]
	v_pk_mul_f32 v[40:41], v[40:41], v[106:107]
	v_pk_mul_f32 v[36:37], v[36:37], v[110:111]
	v_pk_mul_f32 v[46:47], v[46:47], v[104:105]
	v_pk_mul_f32 v[42:43], v[42:43], v[108:109]
	v_pk_mul_f32 v[38:39], v[38:39], v[112:113]
	v_pk_mul_f32 v[34:35], v[34:35], v[116:117]
	v_pk_mul_f32 v[32:33], v[32:33], v[114:115]
	v_pk_mul_f32 v[28:29], v[28:29], v[102:103]
	v_pk_mul_f32 v[24:25], v[24:25], v[106:107]
	v_pk_mul_f32 v[20:21], v[20:21], v[110:111]
	v_pk_mul_f32 v[30:31], v[30:31], v[104:105]
	v_pk_mul_f32 v[26:27], v[26:27], v[108:109]
	v_pk_mul_f32 v[22:23], v[22:23], v[112:113]
	v_pk_mul_f32 v[18:19], v[18:19], v[116:117]
	v_pk_mul_f32 v[16:17], v[16:17], v[114:115]
